# engine-1: PV(sub-chunk0) MFMAs interleaved with sub-chunk1 softmax VALU on a no-rescale fast path (slow path = original order)
# baseline (speedup 1.0000x reference)
.LBB0_590:
	v_mov_b64_e32 v[154:155], v[2:3]
	v_fma_f32 v2, v136, s72, -v152
	v_exp_f32_e32 v136, v2
	v_fma_f32 v2, v137, s72, -v152
	v_exp_f32_e32 v137, v2
	v_fma_f32 v2, v138, s72, -v152
	v_exp_f32_e32 v138, v2
	v_fma_f32 v2, v139, s72, -v152
	v_exp_f32_e32 v139, v2
	v_fma_f32 v2, v132, s72, -v152
	v_exp_f32_e32 v168, v2
	v_fma_f32 v2, v133, s72, -v152
	v_exp_f32_e32 v169, v2
	v_fma_f32 v2, v134, s72, -v152
	v_exp_f32_e32 v170, v2
	v_fma_f32 v2, v135, s72, -v152
	v_exp_f32_e32 v171, v2
	v_pk_add_f32 v[166:167], v[136:137], 0 op_sel_hi:[1,0]
	v_cvt_pk_bf16_f32 v134, v168, v169
	v_pk_add_f32 v[166:167], v[138:139], v[166:167]
	v_fma_f32 v124, v124, s72, -v3
	v_pk_add_f32 v[132:133], v[168:169], v[166:167]
	v_fma_f32 v125, v125, s72, -v3
	v_pk_add_f32 v[132:133], v[170:171], v[132:133]
	v_fma_f32 v126, v126, s72, -v3
	v_add_f32_e32 v2, v132, v133
	v_add_f32_e32 v0, v0, v2
	v_add_u32_e32 v2, s28, v160
	v_add_u32_e32 v152, v2, v159
	ds_read_b128 v[166:169], v152 offset:8192
	v_fma_f32 v127, v127, s72, -v3
	v_fma_f32 v128, v128, s72, -v3
	v_fma_f32 v129, v129, s72, -v3
	v_fma_f32 v130, v130, s72, -v3
	v_fma_f32 v131, v131, s72, -v3
	v_exp_f32_e32 v124, v124
	v_exp_f32_e32 v125, v125
	v_exp_f32_e32 v126, v126
	v_exp_f32_e32 v127, v127
	v_exp_f32_e32 v128, v128
	v_exp_f32_e32 v129, v129
	v_exp_f32_e32 v130, v130
	v_exp_f32_e32 v131, v131
	v_cvt_pk_bf16_f32 v132, v136, v137
	v_cvt_pk_bf16_f32 v133, v138, v139
	v_cvt_pk_bf16_f32 v135, v170, v171
	ds_read_b128 v[170:173], v152 offset:10240
	v_cvt_pk_bf16_f32 v136, v124, v125
	v_cvt_pk_bf16_f32 v137, v126, v127
	v_cvt_pk_bf16_f32 v138, v128, v129
	v_cvt_pk_bf16_f32 v139, v130, v131
	v_pk_add_f32 v[124:125], v[124:125], 0 op_sel_hi:[1,0]
	s_nop 0
	v_pk_add_f32 v[124:125], v[126:127], v[124:125]
	s_nop 0
	v_pk_add_f32 v[124:125], v[128:129], v[124:125]
	s_nop 0
	v_pk_add_f32 v[124:125], v[130:131], v[124:125]
	s_nop 0
	v_add_f32_e32 v124, v124, v125
	ds_read_b128 v[126:129], v152 offset:12288
	v_max3_f32 v125, v116, v117, v118
	v_add_f32_e32 v130, 0x41000000, v165
	v_max3_f32 v125, v125, v119, v120
	s_nop 0
	v_max3_f32 v125, v125, v121, v122
	s_nop 0
	v_max3_f32 v125, v125, v123, v123
	s_nop 0
	v_mul_f32_e32 v125, 0x3e38aa3b, v125
	v_cmp_gt_f32_e32 vcc, v125, v130
	s_cbranch_vccnz .Le1_slow
	v_max3_f32 v125, v108, v109, v110
	v_add_f32_e32 v130, 0x41000000, v3
	v_max3_f32 v125, v125, v111, v112
	s_nop 0
	v_max3_f32 v125, v125, v113, v114
	s_nop 0
	v_max3_f32 v125, v125, v115, v115
	s_nop 0
	v_mul_f32_e32 v125, 0x3e38aa3b, v125
	v_cmp_gt_f32_e32 vcc, v125, v130
	s_cbranch_vccnz .Le1_slow
	s_waitcnt lgkmcnt(2)
	v_mfma_f32_16x16x32_bf16 v[80:83], v[166:169], v[132:135], v[80:83]
	v_fma_f32 v116, v116, s72, -v165
	v_fma_f32 v117, v117, s72, -v165
	v_exp_f32_e32 v116, v116
	v_mfma_f32_16x16x32_bf16 v[76:79], v[166:169], v[136:139], v[76:79]
	v_exp_f32_e32 v117, v117
	v_fma_f32 v118, v118, s72, -v165
	v_fma_f32 v119, v119, s72, -v165
	ds_read_b128 v[166:169], v152 offset:14336
	s_waitcnt lgkmcnt(2)
	v_mfma_f32_16x16x32_bf16 v[72:75], v[170:173], v[132:135], v[72:75]
	v_exp_f32_e32 v118, v118
	v_exp_f32_e32 v119, v119
	v_fma_f32 v120, v120, s72, -v165
	v_mfma_f32_16x16x32_bf16 v[68:71], v[170:173], v[136:139], v[68:71]
	v_fma_f32 v121, v121, s72, -v165
	v_fma_f32 v108, v108, s72, -v3
	v_fma_f32 v109, v109, s72, -v3
	ds_read_b128 v[170:173], v152 offset:16384
	s_waitcnt lgkmcnt(2)
	v_mfma_f32_16x16x32_bf16 v[64:67], v[126:129], v[132:135], v[64:67]
	v_exp_f32_e32 v120, v120
	v_exp_f32_e32 v121, v121
	v_exp_f32_e32 v108, v108
	v_mfma_f32_16x16x32_bf16 v[60:63], v[126:129], v[136:139], v[60:63]
	v_exp_f32_e32 v109, v109
	v_fma_f32 v110, v110, s72, -v3
	v_fma_f32 v111, v111, s72, -v3
	ds_read_b128 v[126:129], v152 offset:18432
	s_waitcnt lgkmcnt(2)
	v_mfma_f32_16x16x32_bf16 v[56:59], v[166:169], v[132:135], v[56:59]
	v_exp_f32_e32 v110, v110
	v_exp_f32_e32 v111, v111
	v_fma_f32 v112, v112, s72, -v3
	v_mfma_f32_16x16x32_bf16 v[52:55], v[166:169], v[136:139], v[52:55]
	v_fma_f32 v113, v113, s72, -v3
	v_pk_add_f32 v[130:131], v[116:117], 0 op_sel_hi:[1,0]
	v_exp_f32_e32 v112, v112
	ds_read_b128 v[166:169], v152 offset:20480
	s_waitcnt lgkmcnt(2)
	v_mfma_f32_16x16x32_bf16 v[48:51], v[170:173], v[132:135], v[48:51]
	v_exp_f32_e32 v113, v113
	v_fma_f32 v114, v114, s72, -v3
	v_fma_f32 v115, v115, s72, -v3
	v_mfma_f32_16x16x32_bf16 v[44:47], v[170:173], v[136:139], v[44:47]
	v_pk_add_f32 v[130:131], v[118:119], v[130:131]
	v_exp_f32_e32 v114, v114
	v_exp_f32_e32 v115, v115
	ds_read_b128 v[170:173], v152 offset:22528
	s_waitcnt lgkmcnt(2)
	v_mfma_f32_16x16x32_bf16 v[40:43], v[126:129], v[132:135], v[40:43]
	v_pk_add_f32 v[130:131], v[120:121], v[130:131]
	v_cvt_pk_bf16_f32 v116, v116, v117
	v_cvt_pk_bf16_f32 v117, v118, v119
	v_mfma_f32_16x16x32_bf16 v[32:35], v[126:129], v[136:139], v[32:35]
	v_cvt_pk_bf16_f32 v118, v120, v121
	v_pk_add_f32 v[120:121], v[108:109], 0 op_sel_hi:[1,0]
	v_add_u32_e32 v2, v2, v157
	s_waitcnt lgkmcnt(1)
	v_mfma_f32_16x16x32_bf16 v[36:39], v[166:169], v[132:135], v[36:39]
	v_pk_add_f32 v[120:121], v[110:111], v[120:121]
	v_cvt_pk_bf16_f32 v108, v108, v109
	v_pk_add_f32 v[120:121], v[112:113], v[120:121]
	v_mfma_f32_16x16x32_bf16 v[24:27], v[166:169], v[136:139], v[24:27]
	v_cvt_pk_bf16_f32 v109, v110, v111
	v_pk_add_f32 v[120:121], v[114:115], v[120:121]
	v_cvt_pk_bf16_f32 v110, v112, v113
	s_waitcnt lgkmcnt(0)
	v_mfma_f32_16x16x32_bf16 v[28:31], v[170:173], v[132:135], v[28:31]
	v_cvt_pk_bf16_f32 v111, v114, v115
	v_mfma_f32_16x16x32_bf16 v[20:23], v[170:173], v[136:139], v[20:23]
	v_mov_b64_e32 v[126:127], v[130:131]
	v_add_f32_e32 v124, v158, v124
	s_branch .Le1_join
.Le1_slow:
	s_waitcnt lgkmcnt(2)
	v_mfma_f32_16x16x32_bf16 v[80:83], v[166:169], v[132:135], v[80:83]
	v_mfma_f32_16x16x32_bf16 v[76:79], v[166:169], v[136:139], v[76:79]
	ds_read_b128 v[166:169], v152 offset:14336
	s_waitcnt lgkmcnt(2)
	v_mfma_f32_16x16x32_bf16 v[72:75], v[170:173], v[132:135], v[72:75]
	v_mfma_f32_16x16x32_bf16 v[68:71], v[170:173], v[136:139], v[68:71]
	ds_read_b128 v[170:173], v152 offset:16384
	s_waitcnt lgkmcnt(2)
	v_mfma_f32_16x16x32_bf16 v[64:67], v[126:129], v[132:135], v[64:67]
	v_mfma_f32_16x16x32_bf16 v[60:63], v[126:129], v[136:139], v[60:63]
	ds_read_b128 v[126:129], v152 offset:18432
	s_waitcnt lgkmcnt(2)
	v_mfma_f32_16x16x32_bf16 v[56:59], v[166:169], v[132:135], v[56:59]
	v_mfma_f32_16x16x32_bf16 v[52:55], v[166:169], v[136:139], v[52:55]
	ds_read_b128 v[166:169], v152 offset:20480
	s_waitcnt lgkmcnt(2)
	v_mfma_f32_16x16x32_bf16 v[48:51], v[170:173], v[132:135], v[48:51]
	v_mfma_f32_16x16x32_bf16 v[44:47], v[170:173], v[136:139], v[44:47]
	ds_read_b128 v[170:173], v152 offset:22528
	s_waitcnt lgkmcnt(2)
	v_mfma_f32_16x16x32_bf16 v[40:43], v[126:129], v[132:135], v[40:43]
	v_mfma_f32_16x16x32_bf16 v[32:35], v[126:129], v[136:139], v[32:35]
	s_waitcnt lgkmcnt(1)
	v_mfma_f32_16x16x32_bf16 v[36:39], v[166:169], v[132:135], v[36:39]
	v_mfma_f32_16x16x32_bf16 v[24:27], v[166:169], v[136:139], v[24:27]
	s_waitcnt lgkmcnt(0)
	v_mfma_f32_16x16x32_bf16 v[28:31], v[170:173], v[132:135], v[28:31]
	v_max3_f32 v132, v116, v117, v118
	v_add_f32_e32 v133, 0x41000000, v165
	v_max3_f32 v132, v132, v119, v120
	v_mfma_f32_16x16x32_bf16 v[20:23], v[170:173], v[136:139], v[20:23]
	v_max3_f32 v132, v132, v121, v122
	s_nop 0
	v_max3_f32 v132, v132, v123, v123
	s_nop 0
	v_mul_f32_e32 v132, 0x3e38aa3b, v132
	v_cmp_gt_f32_e32 vcc, v132, v133
	s_cbranch_vccz .LBB0_592
	ds_swizzle_b32 v3, v132 offset:swizzle(SWAP,16)
	v_max_f32_e32 v132, v132, v132
	s_waitcnt lgkmcnt(0)
	v_max_f32_e32 v3, v3, v3
	v_max_f32_e32 v3, v132, v3
	ds_bpermute_b32 v132, v156, v3
	s_waitcnt lgkmcnt(0)
	v_max3_f32 v154, v165, v3, v132
	v_sub_f32_e32 v3, v165, v154
	v_exp_f32_e32 v132, v3
	v_mov_b32_e32 v3, v155
	v_mov_b32_e32 v165, v154
	v_mul_f32_e32 v0, v0, v132
	v_pk_mul_f32 v[82:83], v[82:83], v[132:133] op_sel_hi:[1,0]
	v_pk_mul_f32 v[80:81], v[80:81], v[132:133] op_sel_hi:[1,0]
	v_pk_mul_f32 v[74:75], v[74:75], v[132:133] op_sel_hi:[1,0]
	v_pk_mul_f32 v[72:73], v[72:73], v[132:133] op_sel_hi:[1,0]
	v_pk_mul_f32 v[66:67], v[66:67], v[132:133] op_sel_hi:[1,0]
	v_pk_mul_f32 v[64:65], v[64:65], v[132:133] op_sel_hi:[1,0]
	v_pk_mul_f32 v[58:59], v[58:59], v[132:133] op_sel_hi:[1,0]
	v_pk_mul_f32 v[56:57], v[56:57], v[132:133] op_sel_hi:[1,0]
	v_pk_mul_f32 v[50:51], v[50:51], v[132:133] op_sel_hi:[1,0]
	v_pk_mul_f32 v[48:49], v[48:49], v[132:133] op_sel_hi:[1,0]
	v_pk_mul_f32 v[42:43], v[42:43], v[132:133] op_sel_hi:[1,0]
	v_pk_mul_f32 v[40:41], v[40:41], v[132:133] op_sel_hi:[1,0]
	v_pk_mul_f32 v[38:39], v[38:39], v[132:133] op_sel_hi:[1,0]
	v_pk_mul_f32 v[36:37], v[36:37], v[132:133] op_sel_hi:[1,0]
	v_pk_mul_f32 v[30:31], v[30:31], v[132:133] op_sel_hi:[1,0]
	v_pk_mul_f32 v[28:29], v[28:29], v[132:133] op_sel_hi:[1,0]

.Le1_join:
	ds_read_b128 v[112:115], v2 offset:8192
	ds_read_b128 v[128:131], v2 offset:10240
	ds_read_b128 v[132:135], v2 offset:12288
	ds_read_b128 v[136:139], v2 offset:14336
	v_fma_f32 v122, v122, s72, -v165
	v_fma_f32 v123, v123, s72, -v165
	v_exp_f32_e32 v122, v122
	v_exp_f32_e32 v123, v123
	s_waitcnt lgkmcnt(3)
	v_mfma_f32_16x16x32_bf16 v[76:79], v[112:115], v[108:111], v[76:79]
	v_cvt_pk_bf16_f32 v119, v122, v123
	s_bitcmp1_b32 s21, 0
	s_cselect_b32 s0, 0x6000, 0
	v_mfma_f32_16x16x32_bf16 v[80:83], v[112:115], v[116:119], v[80:83]
	ds_read_b128 v[112:115], v2 offset:16384
	v_pk_add_f32 v[126:127], v[122:123], v[126:127]
	s_add_i32 s0, s0, 0
	s_waitcnt lgkmcnt(3)
	v_mfma_f32_16x16x32_bf16 v[72:75], v[128:131], v[116:119], v[72:75]
	v_add_f32_e32 v125, v126, v127
	v_add_f32_e32 v120, v120, v121
	v_mov_b64_e32 v[152:153], v[154:155]
	v_mfma_f32_16x16x32_bf16 v[68:71], v[128:131], v[108:111], v[68:71]
	ds_read_b128 v[128:131], v2 offset:18432
	v_add_f32_e32 v0, v0, v125
	v_add_f32_e32 v158, v124, v120
	s_waitcnt lgkmcnt(3)
	v_mfma_f32_16x16x32_bf16 v[64:67], v[132:135], v[116:119], v[64:67]
	s_cmpk_eq_i32 s19, 0x10c0
	v_mfma_f32_16x16x32_bf16 v[60:63], v[132:135], v[108:111], v[60:63]
	ds_read_b128 v[132:135], v2 offset:20480
	s_waitcnt lgkmcnt(3)
	v_mfma_f32_16x16x32_bf16 v[56:59], v[136:139], v[116:119], v[56:59]
	v_mfma_f32_16x16x32_bf16 v[52:55], v[136:139], v[108:111], v[52:55]
	ds_read_b128 v[136:139], v2 offset:22528
	s_waitcnt lgkmcnt(3)
	v_mfma_f32_16x16x32_bf16 v[48:51], v[112:115], v[116:119], v[48:51]
	v_mfma_f32_16x16x32_bf16 v[44:47], v[112:115], v[108:111], v[44:47]
	s_waitcnt lgkmcnt(2)
	v_mfma_f32_16x16x32_bf16 v[40:43], v[128:131], v[116:119], v[40:43]
	v_mfma_f32_16x16x32_bf16 v[32:35], v[128:131], v[108:111], v[32:35]
	v_add_u32_e32 v2, s0, v164
	s_waitcnt vmcnt(5)
	ds_write_b128 v2, v[84:87]
	s_waitcnt vmcnt(4)
	ds_write_b128 v2, v[88:91] offset:4096
	s_waitcnt lgkmcnt(3)
	v_mfma_f32_16x16x32_bf16 v[36:39], v[132:135], v[116:119], v[36:39]
	v_mfma_f32_16x16x32_bf16 v[24:27], v[132:135], v[108:111], v[24:27]
	v_add3_u32 v2, s0, v163, v162
	s_waitcnt vmcnt(3)
	ds_write_b128 v2, v[92:95] offset:8192
	s_waitcnt vmcnt(1)
	ds_write_b128 v2, v[96:99] offset:12288
	s_waitcnt lgkmcnt(4)
	v_mfma_f32_16x16x32_bf16 v[28:31], v[136:139], v[116:119], v[28:31]
	s_waitcnt vmcnt(0)
	ds_write_b128 v2, v[100:103] offset:16384
	ds_write_b128 v2, v[104:107] offset:20480
	v_mfma_f32_16x16x32_bf16 v[20:23], v[136:139], v[108:111], v[20:23]
	s_cbranch_scc1 .LBB0_596
	s_mov_b32 s0, s21
	s_branch .LBB0_580
